# attention workers (GQA and NA loops): 8 K-fragment LDS reads per QK^T block issued together into distinct quads, each MFMA waits for its own fragment
# speedup vs baseline: 1.0140x; 1.0074x over previous
.LBB0_827:
	s_xor_b64 s[0:1], s[34:35], -1
	v_add_u32_e32 v182, v117, v120
	s_and_b64 vcc, exec, s[0:1]
	ds_read_b128 v[34:37], v127
	ds_read_b128 v[212:215], v128
	ds_read_b128 v[216:219], v129
	ds_read_b128 v[220:223], v134
	ds_read_b128 v[224:227], v127 offset:4096
	ds_read_b128 v[138:141], v128 offset:4096
	ds_read_b128 v[228:231], v129 offset:4096
	ds_read_b128 v[232:235], v134 offset:4096
	s_waitcnt vmcnt(11) lgkmcnt(7)
	s_nop 0
	v_mfma_f32_32x32x16_bf16 v[50:65], v[34:37], v[66:69], 0
	s_waitcnt vmcnt(10) lgkmcnt(6)
	s_nop 0
	v_mfma_f32_32x32x16_bf16 v[50:65], v[212:215], v[70:73], v[50:65]
	s_waitcnt vmcnt(9) lgkmcnt(5)
	s_nop 0
	v_mfma_f32_32x32x16_bf16 v[50:65], v[216:219], v[74:77], v[50:65]
	s_waitcnt vmcnt(8) lgkmcnt(4)
	s_nop 0
	v_mfma_f32_32x32x16_bf16 v[50:65], v[220:223], v[78:81], v[50:65]
	s_waitcnt lgkmcnt(3)
	s_nop 0
	v_mfma_f32_32x32x16_bf16 v[34:49], v[224:227], v[66:69], 0
	s_nop 8
	v_max_f32_e32 v0, v51, v51
	s_waitcnt lgkmcnt(2)
	s_nop 0
	v_mfma_f32_32x32x16_bf16 v[34:49], v[138:141], v[70:73], v[34:49]
	s_waitcnt lgkmcnt(1)
	s_nop 0
	v_mfma_f32_32x32x16_bf16 v[34:49], v[228:231], v[74:77], v[34:49]
	s_waitcnt lgkmcnt(0)
	s_nop 0
	v_mfma_f32_32x32x16_bf16 v[34:49], v[232:235], v[78:81], v[34:49]
	v_max_f32_e32 v138, v50, v50
	v_max_f32_e32 v0, v138, v0
	v_max3_f32 v0, v0, v52, v53
	v_max3_f32 v0, v0, v54, v55
	v_max3_f32 v0, v0, v56, v57
	v_max3_f32 v0, v0, v58, v59
	v_max3_f32 v0, v0, v60, v61
	v_max3_f32 v0, v0, v62, v63
	v_max3_f32 v0, v0, v64, v65
	s_nop 2
	v_max3_f32 v0, v0, v34, v35
	v_max3_f32 v0, v0, v36, v37
	v_max3_f32 v0, v0, v38, v39
	v_max3_f32 v0, v0, v40, v41
	v_max3_f32 v0, v0, v42, v43
	v_max3_f32 v0, v0, v44, v45
	v_max3_f32 v0, v0, v46, v47
	v_max3_f32 v0, v0, v48, v49
	ds_bpermute_b32 v138, v126, v0
	s_waitcnt lgkmcnt(0)
	v_max3_f32 v183, v181, v0, v138
	v_sub_f32_e32 v34, v34, v183
	v_exp_f32_e32 v154, v34
	v_sub_f32_e32 v34, v35, v183
	v_exp_f32_e32 v155, v34
	v_sub_f32_e32 v34, v36, v183
	v_exp_f32_e32 v156, v34
	v_sub_f32_e32 v34, v37, v183
	v_sub_f32_e32 v50, v50, v183
	v_exp_f32_e32 v157, v34
	v_sub_f32_e32 v34, v38, v183
	v_exp_f32_e32 v138, v50
	v_sub_f32_e32 v50, v51, v183
	v_exp_f32_e32 v158, v34
	v_sub_f32_e32 v34, v39, v183
	v_exp_f32_e32 v139, v50
	v_sub_f32_e32 v50, v52, v183
	v_exp_f32_e32 v159, v34
	v_sub_f32_e32 v34, v40, v183
	v_exp_f32_e32 v140, v50
	v_sub_f32_e32 v50, v53, v183
	v_exp_f32_e32 v160, v34
	v_sub_f32_e32 v34, v41, v183
	v_exp_f32_e32 v141, v50
	v_sub_f32_e32 v50, v54, v183
	v_exp_f32_e32 v161, v34
	v_sub_f32_e32 v34, v42, v183
	v_exp_f32_e32 v142, v50
	v_sub_f32_e32 v50, v55, v183
	v_exp_f32_e32 v162, v34
	v_sub_f32_e32 v34, v43, v183
	v_exp_f32_e32 v143, v50
	v_sub_f32_e32 v50, v56, v183
	v_exp_f32_e32 v163, v34
	v_sub_f32_e32 v34, v44, v183
	v_sub_f32_e32 v0, v181, v183
	v_exp_f32_e32 v144, v50
	v_sub_f32_e32 v50, v57, v183
	v_exp_f32_e32 v164, v34
	v_sub_f32_e32 v34, v45, v183
	v_exp_f32_e32 v145, v50
	v_exp_f32_e32 v165, v34
	v_sub_f32_e32 v34, v46, v183
	v_exp_f32_e32 v0, v0
	v_add_u32_e32 v46, 0x4000, v135
	v_exp_f32_e32 v166, v34
	v_sub_f32_e32 v34, v47, v183
	ds_read2_b64 v[38:41], v46 offset1:2
	ds_read2_b64 v[42:45], v46 offset0:4 offset1:6
	v_exp_f32_e32 v167, v34
	v_sub_f32_e32 v34, v48, v183
	v_exp_f32_e32 v168, v34
	v_sub_f32_e32 v34, v49, v183
	v_exp_f32_e32 v169, v34
	v_pk_mul_f32 v[32:33], v[32:33], v[0:1] op_sel_hi:[1,0]
	v_pk_mul_f32 v[30:31], v[30:31], v[0:1] op_sel_hi:[1,0]
	v_pk_mul_f32 v[28:29], v[28:29], v[0:1] op_sel_hi:[1,0]
	v_pk_mul_f32 v[26:27], v[26:27], v[0:1] op_sel_hi:[1,0]
	v_pk_mul_f32 v[24:25], v[24:25], v[0:1] op_sel_hi:[1,0]
	v_pk_mul_f32 v[22:23], v[22:23], v[0:1] op_sel_hi:[1,0]
	v_pk_mul_f32 v[20:21], v[20:21], v[0:1] op_sel_hi:[1,0]
	v_pk_mul_f32 v[18:19], v[18:19], v[0:1] op_sel_hi:[1,0]
	v_cvt_pk_bf16_f32 v34, v138, v139
	v_cvt_pk_bf16_f32 v35, v140, v141
	v_cvt_pk_bf16_f32 v36, v142, v143
	v_cvt_pk_bf16_f32 v37, v144, v145
	v_add_u32_e32 v47, 0x5000, v135
	v_sub_f32_e32 v50, v58, v183
	s_waitcnt lgkmcnt(1)
	v_mfma_f32_32x32x16_bf16 v[18:33], v[38:41], v[34:37], v[18:33]
	ds_read2_b64 v[38:41], v47 offset0:32 offset1:34
	v_exp_f32_e32 v146, v50
	v_sub_f32_e32 v50, v59, v183
	v_exp_f32_e32 v147, v50
	v_sub_f32_e32 v50, v60, v183
	v_exp_f32_e32 v148, v50
	v_sub_f32_e32 v50, v61, v183
	v_pk_mul_f32 v[16:17], v[16:17], v[0:1] op_sel_hi:[1,0]
	v_pk_mul_f32 v[14:15], v[14:15], v[0:1] op_sel_hi:[1,0]
	v_pk_mul_f32 v[12:13], v[12:13], v[0:1] op_sel_hi:[1,0]
	v_pk_mul_f32 v[10:11], v[10:11], v[0:1] op_sel_hi:[1,0]
	v_pk_mul_f32 v[8:9], v[8:9], v[0:1] op_sel_hi:[1,0]
	v_pk_mul_f32 v[6:7], v[6:7], v[0:1] op_sel_hi:[1,0]
	v_pk_mul_f32 v[4:5], v[4:5], v[0:1] op_sel_hi:[1,0]
	v_pk_mul_f32 v[2:3], v[2:3], v[0:1] op_sel_hi:[1,0]
	v_exp_f32_e32 v149, v50
	v_sub_f32_e32 v50, v62, v183
	s_waitcnt lgkmcnt(0)
	v_mfma_f32_32x32x16_bf16 v[2:17], v[38:41], v[34:37], v[2:17]
	ds_read2_b64 v[38:41], v47 offset0:36 offset1:38
	v_exp_f32_e32 v150, v50
	v_sub_f32_e32 v50, v63, v183
	v_exp_f32_e32 v151, v50
	v_sub_f32_e32 v50, v64, v183
	v_exp_f32_e32 v152, v50
	v_sub_f32_e32 v50, v65, v183
	v_exp_f32_e32 v153, v50
	v_cvt_pk_bf16_f32 v34, v146, v147
	v_cvt_pk_bf16_f32 v35, v148, v149
	v_cvt_pk_bf16_f32 v36, v150, v151
	v_cvt_pk_bf16_f32 v37, v152, v153
	s_waitcnt lgkmcnt(0)
	s_nop 0
	v_mfma_f32_32x32x16_bf16 v[2:17], v[38:41], v[34:37], v[2:17]
	ds_read2_b64 v[38:41], v46 offset0:8 offset1:10
	v_mfma_f32_32x32x16_bf16 v[18:33], v[42:45], v[34:37], v[18:33]
	v_cvt_pk_bf16_f32 v34, v154, v155
	v_cvt_pk_bf16_f32 v35, v156, v157
	v_cvt_pk_bf16_f32 v36, v158, v159
	v_cvt_pk_bf16_f32 v37, v160, v161
	s_waitcnt lgkmcnt(0)
	s_nop 0
	v_mfma_f32_32x32x16_bf16 v[18:33], v[38:41], v[34:37], v[18:33]
	ds_read2_b64 v[38:41], v47 offset0:40 offset1:42
	s_waitcnt lgkmcnt(0)
	v_mfma_f32_32x32x16_bf16 v[2:17], v[38:41], v[34:37], v[2:17]
	ds_read2_b64 v[38:41], v46 offset0:12 offset1:14
	v_cvt_pk_bf16_f32 v34, v162, v163
	v_cvt_pk_bf16_f32 v35, v164, v165
	v_cvt_pk_bf16_f32 v36, v166, v167
	v_cvt_pk_bf16_f32 v37, v168, v169
	s_waitcnt lgkmcnt(0)
	s_nop 0
	v_mfma_f32_32x32x16_bf16 v[18:33], v[38:41], v[34:37], v[18:33]
	ds_read2_b64 v[38:41], v47 offset0:44 offset1:46
	s_waitcnt vmcnt(2)
	ds_write_b128 v136, v[82:85] offset:8192
	s_waitcnt vmcnt(6)
	ds_write_b128 v182, v[86:89] offset:8192
	s_waitcnt lgkmcnt(2)
	v_mfma_f32_32x32x16_bf16 v[2:17], v[38:41], v[34:37], v[2:17]
	v_add_u32_e32 v34, 0x6200, v121
	s_waitcnt vmcnt(0)
	ds_write2_b64 v34, v[102:103], v[104:105] offset1:1
	v_add_u32_e32 v34, 0x6210, v121
	ds_write2_b64 v34, v[98:99], v[100:101] offset1:1
	s_waitcnt lgkmcnt(0)
	s_barrier
	s_cbranch_vccnz .LBB0_829
	global_load_dwordx4 v[86:89], v[118:119], off offset:16
	global_load_dwordx4 v[82:85], v[118:119], off
	global_load_dwordx4 v[98:101], v[114:115], off offset:400
	global_load_dwordx4 v[102:105], v[114:115], off offset:384
.LBB0_829:
	v_add_u32_e32 v196, 0x6000, v135
	v_add_u32_e32 v197, 0x7000, v135
	s_andn2_b64 vcc, exec, s[34:35]
	ds_read_b128 v[34:37], v127 offset:8192
	ds_read_b128 v[212:215], v128 offset:8192
	ds_read_b128 v[216:219], v129 offset:8192
	ds_read_b128 v[220:223], v134 offset:8192
	ds_read_b128 v[224:227], v127 offset:12288
	ds_read_b128 v[184:187], v128 offset:12288
	ds_read_b128 v[228:231], v129 offset:12288
	ds_read_b128 v[232:235], v134 offset:12288
	s_waitcnt lgkmcnt(7)
	s_nop 0
	v_mfma_f32_32x32x16_bf16 v[50:65], v[34:37], v[66:69], 0
	s_waitcnt lgkmcnt(6)
	s_nop 0
	v_mfma_f32_32x32x16_bf16 v[50:65], v[212:215], v[70:73], v[50:65]
	s_waitcnt lgkmcnt(5)
	s_nop 0
	v_mfma_f32_32x32x16_bf16 v[50:65], v[216:219], v[74:77], v[50:65]
	s_waitcnt lgkmcnt(4)
	s_nop 0
	v_mfma_f32_32x32x16_bf16 v[50:65], v[220:223], v[78:81], v[50:65]
	s_waitcnt lgkmcnt(3)
	s_nop 0
	v_mfma_f32_32x32x16_bf16 v[34:49], v[224:227], v[66:69], 0
	s_nop 8
	v_max_f32_e32 v181, v51, v51
	s_waitcnt lgkmcnt(2)
	s_nop 0
	v_mfma_f32_32x32x16_bf16 v[34:49], v[184:187], v[70:73], v[34:49]
	s_waitcnt lgkmcnt(1)
	s_nop 0
	v_mfma_f32_32x32x16_bf16 v[34:49], v[228:231], v[74:77], v[34:49]
	ds_read2_b64 v[188:191], v196 offset0:64 offset1:66
	ds_read2_b64 v[192:195], v196 offset0:68 offset1:70
	s_waitcnt lgkmcnt(2)
	s_nop 0
	v_mfma_f32_32x32x16_bf16 v[34:49], v[232:235], v[78:81], v[34:49]
	v_max_f32_e32 v184, v50, v50
	v_max_f32_e32 v181, v184, v181
	v_max3_f32 v181, v181, v52, v53
	v_max3_f32 v181, v181, v54, v55
	v_max3_f32 v181, v181, v56, v57
	v_max3_f32 v181, v181, v58, v59
	v_max3_f32 v181, v181, v60, v61
	v_max3_f32 v181, v181, v62, v63
	v_max3_f32 v181, v181, v64, v65
	s_nop 2
	v_max3_f32 v181, v181, v34, v35
	v_max3_f32 v181, v181, v36, v37
	v_max3_f32 v181, v181, v38, v39
	v_max3_f32 v181, v181, v40, v41
	v_max3_f32 v181, v181, v42, v43
	v_max3_f32 v181, v181, v44, v45
	v_max3_f32 v181, v181, v46, v47
	v_max3_f32 v181, v181, v48, v49
	ds_bpermute_b32 v184, v126, v181
	s_waitcnt lgkmcnt(0)
	v_max3_f32 v181, v183, v181, v184
	v_sub_f32_e32 v34, v34, v181
	v_sub_f32_e32 v184, v183, v181
	v_exp_f32_e32 v183, v34
	v_sub_f32_e32 v34, v35, v181
	v_exp_f32_e32 v35, v34
	v_sub_f32_e32 v34, v36, v181
	v_exp_f32_e32 v36, v34
	v_sub_f32_e32 v34, v37, v181
	v_exp_f32_e32 v37, v34
	v_sub_f32_e32 v34, v38, v181
	v_exp_f32_e32 v38, v34
	v_sub_f32_e32 v34, v39, v181
	v_exp_f32_e32 v39, v34
	v_sub_f32_e32 v34, v40, v181
	v_exp_f32_e32 v40, v34
	v_sub_f32_e32 v34, v41, v181
	v_exp_f32_e32 v41, v34
	v_sub_f32_e32 v34, v42, v181
	v_exp_f32_e32 v42, v34
	v_sub_f32_e32 v34, v43, v181
	v_exp_f32_e32 v43, v34
	v_sub_f32_e32 v34, v44, v181
	v_exp_f32_e32 v44, v34
	v_sub_f32_e32 v34, v45, v181
	v_exp_f32_e32 v45, v34
	v_sub_f32_e32 v34, v46, v181
	v_exp_f32_e32 v46, v34
	v_sub_f32_e32 v34, v47, v181
	v_exp_f32_e32 v47, v34
	v_sub_f32_e32 v34, v48, v181
	v_sub_f32_e32 v50, v50, v181
	v_sub_f32_e32 v51, v51, v181
	v_sub_f32_e32 v52, v52, v181
	v_sub_f32_e32 v53, v53, v181
	v_sub_f32_e32 v54, v54, v181
	v_sub_f32_e32 v55, v55, v181
	v_sub_f32_e32 v56, v56, v181
	v_sub_f32_e32 v57, v57, v181
	v_exp_f32_e32 v48, v34
	v_sub_f32_e32 v34, v49, v181
	v_exp_f32_e32 v50, v50
	v_exp_f32_e32 v51, v51
	v_exp_f32_e32 v52, v52
	v_exp_f32_e32 v53, v53
	v_exp_f32_e32 v54, v54
	v_exp_f32_e32 v55, v55
	v_exp_f32_e32 v56, v56
	v_exp_f32_e32 v57, v57
	v_exp_f32_e32 v49, v34
	v_exp_f32_e32 v34, v184
	v_cvt_pk_bf16_f32 v184, v50, v51
	v_cvt_pk_bf16_f32 v185, v52, v53
	v_cvt_pk_bf16_f32 v186, v54, v55
	v_pk_mul_f32 v[32:33], v[32:33], v[34:35] op_sel_hi:[1,0]
	v_pk_mul_f32 v[30:31], v[30:31], v[34:35] op_sel_hi:[1,0]
	v_pk_mul_f32 v[28:29], v[28:29], v[34:35] op_sel_hi:[1,0]
	v_pk_mul_f32 v[26:27], v[26:27], v[34:35] op_sel_hi:[1,0]
	v_pk_mul_f32 v[24:25], v[24:25], v[34:35] op_sel_hi:[1,0]
	v_pk_mul_f32 v[22:23], v[22:23], v[34:35] op_sel_hi:[1,0]
	v_pk_mul_f32 v[20:21], v[20:21], v[34:35] op_sel_hi:[1,0]
	v_pk_mul_f32 v[18:19], v[18:19], v[34:35] op_sel_hi:[1,0]
	v_cvt_pk_bf16_f32 v187, v56, v57
	v_pk_mul_f32 v[16:17], v[16:17], v[34:35] op_sel_hi:[1,0]
	v_pk_mul_f32 v[14:15], v[14:15], v[34:35] op_sel_hi:[1,0]
	v_mfma_f32_32x32x16_bf16 v[18:33], v[188:191], v[184:187], v[18:33]
	ds_read2_b64 v[188:191], v197 offset0:96 offset1:98
	v_mul_f32_e64 v12, v12, v34
	v_mul_f32_e64 v13, v13, v34
	v_mul_f32_e64 v10, v10, v34
	v_mul_f32_e64 v11, v11, v34
	v_pk_mul_f32 v[8:9], v[8:9], v[34:35] op_sel_hi:[1,0]
	v_pk_mul_f32 v[6:7], v[6:7], v[34:35] op_sel_hi:[1,0]
	v_pk_mul_f32 v[4:5], v[4:5], v[34:35] op_sel_hi:[1,0]
	v_pk_mul_f32 v[2:3], v[2:3], v[34:35] op_sel_hi:[1,0]
	v_sub_f32_e32 v58, v58, v181
	v_sub_f32_e32 v59, v59, v181
	s_waitcnt lgkmcnt(0)
	v_mfma_f32_32x32x16_bf16 v[2:17], v[188:191], v[184:187], v[2:17]
	ds_read2_b64 v[188:191], v197 offset0:100 offset1:102
	v_sub_f32_e32 v60, v60, v181
	v_sub_f32_e32 v61, v61, v181
	v_sub_f32_e32 v62, v62, v181
	v_sub_f32_e32 v63, v63, v181
	v_sub_f32_e32 v64, v64, v181
	v_sub_f32_e32 v65, v65, v181
	v_exp_f32_e32 v58, v58
	v_exp_f32_e32 v59, v59
	v_exp_f32_e32 v60, v60
	v_exp_f32_e32 v61, v61
	v_exp_f32_e32 v62, v62
	v_exp_f32_e32 v63, v63
	v_exp_f32_e32 v64, v64
	v_exp_f32_e32 v65, v65
	v_cvt_pk_bf16_f32 v184, v58, v59
	v_cvt_pk_bf16_f32 v185, v60, v61
	v_cvt_pk_bf16_f32 v186, v62, v63
	v_cvt_pk_bf16_f32 v187, v64, v65
	s_waitcnt lgkmcnt(0)
	s_nop 0
	v_mfma_f32_32x32x16_bf16 v[2:17], v[188:191], v[184:187], v[2:17]
	ds_read2_b64 v[188:191], v196 offset0:72 offset1:74
	v_mfma_f32_32x32x16_bf16 v[18:33], v[192:195], v[184:187], v[18:33]
	v_cvt_pk_bf16_f32 v184, v183, v35
	v_cvt_pk_bf16_f32 v185, v36, v37
	v_cvt_pk_bf16_f32 v186, v38, v39
	v_cvt_pk_bf16_f32 v187, v40, v41
	s_waitcnt lgkmcnt(0)
	s_nop 0
	v_mfma_f32_32x32x16_bf16 v[18:33], v[188:191], v[184:187], v[18:33]
	ds_read2_b64 v[188:191], v197 offset0:104 offset1:106
	s_waitcnt lgkmcnt(0)
	v_mfma_f32_32x32x16_bf16 v[2:17], v[188:191], v[184:187], v[2:17]
	ds_read2_b64 v[188:191], v196 offset0:76 offset1:78
	v_cvt_pk_bf16_f32 v184, v42, v43
	v_cvt_pk_bf16_f32 v185, v44, v45
	v_cvt_pk_bf16_f32 v186, v46, v47
	v_cvt_pk_bf16_f32 v187, v48, v49
	s_waitcnt lgkmcnt(0)
	s_nop 0
	v_mfma_f32_32x32x16_bf16 v[18:33], v[188:191], v[184:187], v[18:33]
	ds_read2_b64 v[188:191], v197 offset0:108 offset1:110
	s_waitcnt lgkmcnt(0)
	v_mfma_f32_32x32x16_bf16 v[2:17], v[188:191], v[184:187], v[2:17]
	s_cbranch_vccnz .LBB0_826
	s_waitcnt vmcnt(3)
	ds_write_b128 v136, v[90:93]
	s_waitcnt vmcnt(2)
	ds_write_b128 v182, v[94:97]
	s_waitcnt vmcnt(0)
	ds_write2_b64 v122, v[110:111], v[112:113] offset1:1
	ds_write2_b64 v123, v[106:107], v[108:109] offset1:1
	s_branch .LBB0_826

.LBB0_861:
	s_add_i32 s0, s97, -4
	s_cmp_lt_i32 s0, s6
	s_cselect_b64 s[2:3], -1, 0
	s_add_i32 s43, s7, s97
	s_add_i32 s0, s43, -4
	v_cmp_lt_u32_e32 vcc, s0, v147
	v_cmp_ge_u32_e64 s[0:1], s0, v148
	s_or_b64 s[0:1], vcc, s[0:1]
	v_cndmask_b32_e64 v0, 0, 1, s[2:3]
	s_and_b64 s[0:1], s[2:3], s[0:1]
	s_xor_b64 s[2:3], s[0:1], -1
	v_cmp_ne_u32_e64 s[46:47], 1, v0
	s_and_saveexec_b64 s[0:1], s[2:3]
	s_cbranch_execz .LBB0_930
	v_add_u32_e32 v0, v149, v150
	v_add_u32_e32 v6, v149, v151
	v_add_u32_e32 v7, v149, v152
	v_add_u32_e32 v8, v149, v153
	s_and_b64 vcc, exec, s[46:47]
	ds_read_b128 v[2:5], v0
	ds_read_b128 v[10:13], v6
	ds_read_b128 v[212:215], v7
	ds_read_b128 v[216:219], v8
	ds_read_b128 v[220:223], v0 offset:4096
	ds_read_b128 v[224:227], v6 offset:4096
	ds_read_b128 v[228:231], v7 offset:4096
	ds_read_b128 v[232:235], v8 offset:4096
	s_waitcnt lgkmcnt(7)
	s_nop 0
	v_mfma_f32_32x32x16_bf16 v[64:79], v[2:5], v[80:83], 0
	s_waitcnt lgkmcnt(6)
	s_nop 0
	v_mfma_f32_32x32x16_bf16 v[64:79], v[10:13], v[84:87], v[64:79]
	s_waitcnt lgkmcnt(5)
	s_nop 0
	v_mfma_f32_32x32x16_bf16 v[64:79], v[212:215], v[88:91], v[64:79]
	s_waitcnt lgkmcnt(4)
	s_nop 0
	v_mfma_f32_32x32x16_bf16 v[64:79], v[216:219], v[92:95], v[64:79]
	s_waitcnt lgkmcnt(3)
	s_nop 0
	v_mfma_f32_32x32x16_bf16 v[48:63], v[220:223], v[80:83], 0
	s_waitcnt lgkmcnt(2)
	s_nop 0
	v_mfma_f32_32x32x16_bf16 v[48:63], v[224:227], v[84:87], v[48:63]
	s_waitcnt lgkmcnt(1)
	s_nop 0
	v_mfma_f32_32x32x16_bf16 v[48:63], v[228:231], v[88:91], v[48:63]
	s_waitcnt lgkmcnt(0)
	s_nop 0
	v_mfma_f32_32x32x16_bf16 v[48:63], v[232:235], v[92:95], v[48:63]
	s_cbranch_vccnz .LBB0_928
	v_mov_b32_e32 v2, 0xff800000
	v_mov_b32_e32 v3, 0xff800000
	s_and_saveexec_b64 s[2:3], s[54:55]
	s_cbranch_execz .LBB0_865
	v_add_u32_e32 v0, v156, v155
	ds_read_b32 v0, v0 offset:34720
	s_waitcnt lgkmcnt(0)
	v_add_f32_e32 v3, v64, v0

.LBB0_946:
	s_cmp_lt_i32 s48, s6
	s_cselect_b64 s[2:3], -1, 0
	s_add_i32 s43, s43, -3
	v_cmp_lt_u32_e32 vcc, s43, v147
	v_cmp_ge_u32_e64 s[0:1], s43, v148
	s_or_b64 s[0:1], vcc, s[0:1]
	s_and_b64 s[0:1], s[2:3], s[0:1]
	s_xor_b64 s[4:5], s[0:1], -1
	s_and_saveexec_b64 s[0:1], s[4:5]
	s_cbranch_execz .LBB0_1015
	v_add_u32_e32 v6, v149, v150
	v_add_u32_e32 v7, v149, v151
	v_add_u32_e32 v8, v149, v152
	v_add_u32_e32 v9, v149, v153
	s_andn2_b64 vcc, exec, s[2:3]
	ds_read_b128 v[2:5], v6 offset:8192
	ds_read_b128 v[10:13], v7 offset:8192
	ds_read_b128 v[212:215], v8 offset:8192
	ds_read_b128 v[216:219], v9 offset:8192
	ds_read_b128 v[220:223], v6 offset:12288
	ds_read_b128 v[224:227], v7 offset:12288
	ds_read_b128 v[228:231], v8 offset:12288
	ds_read_b128 v[232:235], v9 offset:12288
	s_waitcnt lgkmcnt(7)
	s_nop 0
	v_mfma_f32_32x32x16_bf16 v[64:79], v[2:5], v[80:83], 0
	s_waitcnt lgkmcnt(6)
	s_nop 0
	v_mfma_f32_32x32x16_bf16 v[64:79], v[10:13], v[84:87], v[64:79]
	s_waitcnt lgkmcnt(5)
	s_nop 0
	v_mfma_f32_32x32x16_bf16 v[64:79], v[212:215], v[88:91], v[64:79]
	s_waitcnt lgkmcnt(4)
	s_nop 0
	v_mfma_f32_32x32x16_bf16 v[64:79], v[216:219], v[92:95], v[64:79]
	s_waitcnt lgkmcnt(3)
	s_nop 0
	v_mfma_f32_32x32x16_bf16 v[48:63], v[220:223], v[80:83], 0
	s_waitcnt lgkmcnt(2)
	s_nop 0
	v_mfma_f32_32x32x16_bf16 v[48:63], v[224:227], v[84:87], v[48:63]
	s_waitcnt lgkmcnt(1)
	s_nop 0
	v_mfma_f32_32x32x16_bf16 v[48:63], v[228:231], v[88:91], v[48:63]
	s_waitcnt lgkmcnt(0)
	s_nop 0
	v_mfma_f32_32x32x16_bf16 v[48:63], v[232:235], v[92:95], v[48:63]
	s_cbranch_vccnz .LBB0_1013
	v_mov_b32_e32 v3, 0xff800000
	v_add_u32_e32 v2, v156, v155
	v_mov_b32_e32 v4, 0xff800000
	s_and_saveexec_b64 s[2:3], s[54:55]
	s_cbranch_execz .LBB0_950
	ds_read_b32 v4, v2 offset:34844
	s_waitcnt lgkmcnt(0)
	v_add_f32_e32 v4, v64, v4

.LBB0_1022:
	s_add_i32 s4, s4, 2
	v_add_u32_e32 v188, v115, v121
	s_cmp_gt_u32 s4, 64
	ds_read_b128 v[34:37], v136
	ds_read_b128 v[212:215], v137
	ds_read_b128 v[216:219], v138
	ds_read_b128 v[220:223], v139
	ds_read_b128 v[224:227], v136 offset:4096
	ds_read_b128 v[122:125], v137 offset:4096
	ds_read_b128 v[228:231], v138 offset:4096
	ds_read_b128 v[232:235], v139 offset:4096
	s_waitcnt vmcnt(11) lgkmcnt(7)
	s_nop 0
	v_mfma_f32_32x32x16_bf16 v[50:65], v[34:37], v[66:69], 0
	s_waitcnt vmcnt(10) lgkmcnt(6)
	s_nop 0
	v_mfma_f32_32x32x16_bf16 v[50:65], v[212:215], v[70:73], v[50:65]
	s_waitcnt vmcnt(9) lgkmcnt(5)
	s_nop 0
	v_mfma_f32_32x32x16_bf16 v[50:65], v[216:219], v[74:77], v[50:65]
	s_waitcnt vmcnt(8) lgkmcnt(4)
	s_nop 0
	v_mfma_f32_32x32x16_bf16 v[50:65], v[220:223], v[78:81], v[50:65]
	s_waitcnt lgkmcnt(3)
	s_nop 0
	v_mfma_f32_32x32x16_bf16 v[34:49], v[224:227], v[66:69], 0
	s_nop 8
	v_max_f32_e32 v120, v51, v51
	s_waitcnt lgkmcnt(2)
	s_nop 0
	v_mfma_f32_32x32x16_bf16 v[34:49], v[122:125], v[70:73], v[34:49]
	s_waitcnt lgkmcnt(1)
	s_nop 0
	v_mfma_f32_32x32x16_bf16 v[34:49], v[228:231], v[74:77], v[34:49]
	s_waitcnt lgkmcnt(0)
	s_nop 0
	v_mfma_f32_32x32x16_bf16 v[34:49], v[232:235], v[78:81], v[34:49]
	v_max_f32_e32 v122, v50, v50
	v_max_f32_e32 v120, v122, v120
	v_max3_f32 v120, v120, v52, v53
	v_max3_f32 v120, v120, v54, v55
	v_max3_f32 v120, v120, v56, v57
	v_max3_f32 v120, v120, v58, v59
	v_max3_f32 v120, v120, v60, v61
	v_max3_f32 v120, v120, v62, v63
	v_max3_f32 v120, v120, v64, v65
	s_nop 2
	v_max3_f32 v120, v120, v34, v35
	v_max3_f32 v120, v120, v36, v37
	v_max3_f32 v120, v120, v38, v39
	v_max3_f32 v120, v120, v40, v41
	v_max3_f32 v120, v120, v42, v43
	v_max3_f32 v120, v120, v44, v45
	v_max3_f32 v120, v120, v46, v47
	v_max3_f32 v120, v120, v48, v49
	ds_bpermute_b32 v122, v135, v120
	v_lshl_add_u64 v[124:125], v[116:117], 0, v[0:1]
	s_waitcnt lgkmcnt(0)
	v_max3_f32 v187, v186, v120, v122
	v_sub_f32_e32 v34, v34, v187
	v_exp_f32_e32 v159, v34
	v_sub_f32_e32 v34, v35, v187
	v_exp_f32_e32 v160, v34
	v_sub_f32_e32 v34, v36, v187
	v_exp_f32_e32 v161, v34
	v_sub_f32_e32 v34, v37, v187
	v_sub_f32_e32 v50, v50, v187
	v_exp_f32_e32 v162, v34
	v_sub_f32_e32 v34, v38, v187
	v_exp_f32_e32 v143, v50
	v_sub_f32_e32 v50, v51, v187
	v_exp_f32_e32 v163, v34
	v_sub_f32_e32 v34, v39, v187
	v_exp_f32_e32 v144, v50
	v_sub_f32_e32 v50, v52, v187
	v_exp_f32_e32 v164, v34
	v_sub_f32_e32 v34, v40, v187
	v_exp_f32_e32 v145, v50
	v_sub_f32_e32 v50, v53, v187
	v_exp_f32_e32 v165, v34
	v_sub_f32_e32 v34, v41, v187
	v_exp_f32_e32 v146, v50
	v_sub_f32_e32 v50, v54, v187
	v_exp_f32_e32 v166, v34
	v_sub_f32_e32 v34, v42, v187
	v_exp_f32_e32 v147, v50
	v_sub_f32_e32 v50, v55, v187
	v_exp_f32_e32 v167, v34
	v_sub_f32_e32 v34, v43, v187
	v_exp_f32_e32 v148, v50
	v_sub_f32_e32 v50, v56, v187
	v_exp_f32_e32 v168, v34
	v_sub_f32_e32 v34, v44, v187
	v_sub_f32_e32 v120, v186, v187
	v_exp_f32_e32 v149, v50
	v_sub_f32_e32 v50, v57, v187
	v_exp_f32_e32 v169, v34
	v_sub_f32_e32 v34, v45, v187
	v_exp_f32_e32 v150, v50
	v_exp_f32_e32 v181, v34
	v_sub_f32_e32 v34, v46, v187
	v_exp_f32_e32 v120, v120
	v_add_u32_e32 v46, 0x4000, v140
	v_exp_f32_e32 v182, v34
	v_sub_f32_e32 v34, v47, v187
	ds_read2_b64 v[38:41], v46 offset1:2
	ds_read2_b64 v[42:45], v46 offset0:4 offset1:6
	v_exp_f32_e32 v183, v34
	v_sub_f32_e32 v34, v48, v187
	v_exp_f32_e32 v184, v34
	v_sub_f32_e32 v34, v49, v187
	v_exp_f32_e32 v185, v34
	v_pk_mul_f32 v[32:33], v[32:33], v[120:121] op_sel_hi:[1,0]
	v_pk_mul_f32 v[30:31], v[30:31], v[120:121] op_sel_hi:[1,0]
	v_pk_mul_f32 v[28:29], v[28:29], v[120:121] op_sel_hi:[1,0]
	v_pk_mul_f32 v[26:27], v[26:27], v[120:121] op_sel_hi:[1,0]
	v_pk_mul_f32 v[24:25], v[24:25], v[120:121] op_sel_hi:[1,0]
	v_pk_mul_f32 v[22:23], v[22:23], v[120:121] op_sel_hi:[1,0]
	v_pk_mul_f32 v[20:21], v[20:21], v[120:121] op_sel_hi:[1,0]
	v_pk_mul_f32 v[18:19], v[18:19], v[120:121] op_sel_hi:[1,0]
	v_cvt_pk_bf16_f32 v34, v143, v144
	v_cvt_pk_bf16_f32 v35, v145, v146
	v_cvt_pk_bf16_f32 v36, v147, v148
	v_cvt_pk_bf16_f32 v37, v149, v150
	v_add_u32_e32 v47, 0x5000, v140
	v_sub_f32_e32 v50, v58, v187
	s_waitcnt lgkmcnt(1)
	v_mfma_f32_32x32x16_bf16 v[18:33], v[38:41], v[34:37], v[18:33]
	ds_read2_b64 v[38:41], v47 offset0:32 offset1:34
	v_exp_f32_e32 v151, v50
	v_sub_f32_e32 v50, v59, v187
	v_exp_f32_e32 v152, v50
	v_sub_f32_e32 v50, v60, v187
	v_exp_f32_e32 v153, v50
	v_sub_f32_e32 v50, v61, v187
	v_pk_mul_f32 v[16:17], v[16:17], v[120:121] op_sel_hi:[1,0]
	v_pk_mul_f32 v[14:15], v[14:15], v[120:121] op_sel_hi:[1,0]
	v_pk_mul_f32 v[12:13], v[12:13], v[120:121] op_sel_hi:[1,0]
	v_pk_mul_f32 v[10:11], v[10:11], v[120:121] op_sel_hi:[1,0]
	v_pk_mul_f32 v[8:9], v[8:9], v[120:121] op_sel_hi:[1,0]
	v_pk_mul_f32 v[6:7], v[6:7], v[120:121] op_sel_hi:[1,0]
	v_pk_mul_f32 v[4:5], v[4:5], v[120:121] op_sel_hi:[1,0]
	v_pk_mul_f32 v[2:3], v[2:3], v[120:121] op_sel_hi:[1,0]
	v_exp_f32_e32 v154, v50
	v_sub_f32_e32 v50, v62, v187
	s_waitcnt lgkmcnt(0)
	v_mfma_f32_32x32x16_bf16 v[2:17], v[38:41], v[34:37], v[2:17]
	ds_read2_b64 v[38:41], v47 offset0:36 offset1:38
	v_exp_f32_e32 v155, v50
	v_sub_f32_e32 v50, v63, v187
	v_exp_f32_e32 v156, v50
	v_sub_f32_e32 v50, v64, v187
	v_exp_f32_e32 v157, v50
	v_sub_f32_e32 v50, v65, v187
	v_exp_f32_e32 v158, v50
	v_cvt_pk_bf16_f32 v34, v151, v152
	v_cvt_pk_bf16_f32 v35, v153, v154
	v_cvt_pk_bf16_f32 v36, v155, v156
	v_cvt_pk_bf16_f32 v37, v157, v158
	v_lshl_add_u64 v[122:123], v[118:119], 0, v[0:1]
	s_waitcnt lgkmcnt(0)
	v_mfma_f32_32x32x16_bf16 v[2:17], v[38:41], v[34:37], v[2:17]
	ds_read2_b64 v[38:41], v46 offset0:8 offset1:10
	v_mfma_f32_32x32x16_bf16 v[18:33], v[42:45], v[34:37], v[18:33]
	v_cvt_pk_bf16_f32 v34, v159, v160
	v_cvt_pk_bf16_f32 v35, v161, v162
	v_cvt_pk_bf16_f32 v36, v163, v164
	v_cvt_pk_bf16_f32 v37, v165, v166
	s_waitcnt lgkmcnt(0)
	s_nop 0
	v_mfma_f32_32x32x16_bf16 v[18:33], v[38:41], v[34:37], v[18:33]
	ds_read2_b64 v[38:41], v47 offset0:40 offset1:42
	s_waitcnt lgkmcnt(0)
	v_mfma_f32_32x32x16_bf16 v[2:17], v[38:41], v[34:37], v[2:17]
	ds_read2_b64 v[38:41], v46 offset0:12 offset1:14
	v_cvt_pk_bf16_f32 v34, v167, v168
	v_cvt_pk_bf16_f32 v35, v169, v181
	v_cvt_pk_bf16_f32 v36, v182, v183
	v_cvt_pk_bf16_f32 v37, v184, v185
	s_waitcnt lgkmcnt(0)
	s_nop 0
	v_mfma_f32_32x32x16_bf16 v[18:33], v[38:41], v[34:37], v[18:33]
	ds_read2_b64 v[38:41], v47 offset0:44 offset1:46
	s_waitcnt vmcnt(3)
	ds_write_b128 v141, v[82:85] offset:8192
	s_waitcnt vmcnt(2)
	ds_write_b128 v188, v[86:89] offset:8192
	s_waitcnt lgkmcnt(2)
	v_mfma_f32_32x32x16_bf16 v[2:17], v[38:41], v[34:37], v[2:17]
	v_add_u32_e32 v34, 0x6200, v126
	s_waitcnt vmcnt(0)
	ds_write2_b64 v34, v[102:103], v[104:105] offset1:1
	v_add_u32_e32 v34, 0x6210, v126
	ds_write2_b64 v34, v[94:95], v[96:97] offset1:1
	s_waitcnt lgkmcnt(0)
	s_barrier
	s_cbranch_scc1 .LBB0_1024
	v_add_co_u32_e32 v36, vcc, 0x6000, v124
	s_mov_b64 s[0:1], 0x6000
	s_nop 0
	v_addc_co_u32_e32 v37, vcc, 0, v125, vcc
	v_lshl_add_u64 v[34:35], v[124:125], 0, s[0:1]
	global_load_dwordx4 v[82:85], v[36:37], off
	global_load_dwordx4 v[86:89], v[34:35], off offset:16
	global_load_dwordx4 v[94:97], v[122:123], off offset:400
	global_load_dwordx4 v[102:105], v[122:123], off offset:384
.LBB0_1024:
	v_add_u32_e32 v202, 0x7000, v140
	s_cmpk_gt_u32 s4, 0x41
	s_cselect_b64 s[0:1], -1, 0
	s_and_b64 vcc, exec, s[0:1]
	ds_read_b128 v[34:37], v136 offset:8192
	ds_read_b128 v[212:215], v137 offset:8192
	ds_read_b128 v[216:219], v138 offset:8192
	ds_read_b128 v[220:223], v139 offset:8192
	ds_read_b128 v[224:227], v136 offset:12288
	ds_read_b128 v[190:193], v137 offset:12288
	ds_read_b128 v[228:231], v138 offset:12288
	ds_read_b128 v[232:235], v139 offset:12288
	s_waitcnt lgkmcnt(7)
	s_nop 0
	v_mfma_f32_32x32x16_bf16 v[50:65], v[34:37], v[66:69], 0
	s_waitcnt lgkmcnt(6)
	s_nop 0
	v_mfma_f32_32x32x16_bf16 v[50:65], v[212:215], v[70:73], v[50:65]
	s_waitcnt lgkmcnt(5)
	s_nop 0
	v_mfma_f32_32x32x16_bf16 v[50:65], v[216:219], v[74:77], v[50:65]
	s_waitcnt lgkmcnt(4)
	s_nop 0
	v_mfma_f32_32x32x16_bf16 v[50:65], v[220:223], v[78:81], v[50:65]
	s_waitcnt lgkmcnt(3)
	s_nop 0
	v_mfma_f32_32x32x16_bf16 v[34:49], v[224:227], v[66:69], 0
	s_nop 8
	v_max_f32_e32 v186, v51, v51
	v_max_f32_e32 v189, v50, v50
	v_max_f32_e32 v186, v189, v186
	v_max3_f32 v186, v186, v52, v53
	v_max3_f32 v186, v186, v54, v55
	v_max3_f32 v186, v186, v56, v57
	v_max3_f32 v186, v186, v58, v59
	s_waitcnt lgkmcnt(2)
	s_nop 0
	v_mfma_f32_32x32x16_bf16 v[34:49], v[190:193], v[70:73], v[34:49]
	v_max3_f32 v186, v186, v60, v61
	v_max3_f32 v186, v186, v62, v63
	v_max3_f32 v186, v186, v64, v65
	s_waitcnt lgkmcnt(1)
	s_nop 0
	v_mfma_f32_32x32x16_bf16 v[34:49], v[228:231], v[74:77], v[34:49]
	s_waitcnt lgkmcnt(0)
	s_nop 0
	v_mfma_f32_32x32x16_bf16 v[34:49], v[232:235], v[78:81], v[34:49]
	s_nop 11
	v_max3_f32 v186, v186, v34, v35
	v_max3_f32 v186, v186, v36, v37
	v_max3_f32 v186, v186, v38, v39
	v_max3_f32 v186, v186, v40, v41
	v_max3_f32 v186, v186, v42, v43
	v_max3_f32 v186, v186, v44, v45
	v_max3_f32 v186, v186, v46, v47
	v_max3_f32 v186, v186, v48, v49
	ds_bpermute_b32 v189, v135, v186
	s_waitcnt lgkmcnt(0)
	v_max3_f32 v186, v187, v186, v189
	v_sub_f32_e32 v34, v34, v186
	v_sub_f32_e32 v189, v187, v186
	v_exp_f32_e32 v187, v34
	v_sub_f32_e32 v34, v35, v186
	v_exp_f32_e32 v35, v34
	v_sub_f32_e32 v34, v36, v186
	v_exp_f32_e32 v36, v34
	v_sub_f32_e32 v34, v37, v186
	v_exp_f32_e32 v37, v34
	v_sub_f32_e32 v34, v38, v186
	v_exp_f32_e32 v38, v34
	v_sub_f32_e32 v34, v39, v186
	v_exp_f32_e32 v39, v34
	v_sub_f32_e32 v34, v40, v186
	v_exp_f32_e32 v40, v34
	v_sub_f32_e32 v34, v41, v186
	v_exp_f32_e32 v41, v34
	v_sub_f32_e32 v34, v42, v186
	v_exp_f32_e32 v42, v34
	v_sub_f32_e32 v34, v43, v186
	v_exp_f32_e32 v43, v34
	v_sub_f32_e32 v34, v44, v186
	v_exp_f32_e32 v44, v34
	v_sub_f32_e32 v34, v45, v186
	v_exp_f32_e32 v45, v34
	v_sub_f32_e32 v34, v46, v186
	v_exp_f32_e32 v46, v34
	v_sub_f32_e32 v34, v47, v186
	v_exp_f32_e32 v47, v34
	v_sub_f32_e32 v34, v48, v186
	v_sub_f32_e32 v50, v50, v186
	v_sub_f32_e32 v51, v51, v186
	v_sub_f32_e32 v52, v52, v186
	v_sub_f32_e32 v53, v53, v186
	v_sub_f32_e32 v54, v54, v186
	v_sub_f32_e32 v55, v55, v186
	v_sub_f32_e32 v56, v56, v186
	v_sub_f32_e32 v57, v57, v186
	v_exp_f32_e32 v48, v34
	v_sub_f32_e32 v34, v49, v186
	v_exp_f32_e32 v50, v50
	v_exp_f32_e32 v51, v51
	v_exp_f32_e32 v52, v52
	v_exp_f32_e32 v53, v53
	v_exp_f32_e32 v54, v54
	v_exp_f32_e32 v55, v55
	v_exp_f32_e32 v56, v56
	v_exp_f32_e32 v57, v57
	v_exp_f32_e32 v49, v34
	v_exp_f32_e32 v34, v189
	v_add_u32_e32 v189, 0x6000, v140
	ds_read2_b64 v[194:197], v189 offset0:64 offset1:66
	ds_read2_b64 v[198:201], v189 offset0:68 offset1:70
	v_cvt_pk_bf16_f32 v190, v50, v51
	v_pk_mul_f32 v[32:33], v[32:33], v[34:35] op_sel_hi:[1,0]
	v_pk_mul_f32 v[30:31], v[30:31], v[34:35] op_sel_hi:[1,0]
	v_pk_mul_f32 v[28:29], v[28:29], v[34:35] op_sel_hi:[1,0]
	v_pk_mul_f32 v[26:27], v[26:27], v[34:35] op_sel_hi:[1,0]
	v_pk_mul_f32 v[24:25], v[24:25], v[34:35] op_sel_hi:[1,0]
	v_pk_mul_f32 v[22:23], v[22:23], v[34:35] op_sel_hi:[1,0]
	v_pk_mul_f32 v[20:21], v[20:21], v[34:35] op_sel_hi:[1,0]
	v_pk_mul_f32 v[18:19], v[18:19], v[34:35] op_sel_hi:[1,0]
	v_cvt_pk_bf16_f32 v191, v52, v53
	v_cvt_pk_bf16_f32 v192, v54, v55
	v_cvt_pk_bf16_f32 v193, v56, v57
	v_pk_mul_f32 v[16:17], v[16:17], v[34:35] op_sel_hi:[1,0]
	v_pk_mul_f32 v[14:15], v[14:15], v[34:35] op_sel_hi:[1,0]
	s_waitcnt lgkmcnt(1)
	v_mfma_f32_32x32x16_bf16 v[18:33], v[194:197], v[190:193], v[18:33]
	ds_read2_b64 v[194:197], v202 offset0:96 offset1:98
	v_mul_f32_e64 v12, v12, v34
	v_mul_f32_e64 v13, v13, v34
	v_mul_f32_e64 v10, v10, v34
	v_mul_f32_e64 v11, v11, v34
	v_pk_mul_f32 v[8:9], v[8:9], v[34:35] op_sel_hi:[1,0]
	v_pk_mul_f32 v[6:7], v[6:7], v[34:35] op_sel_hi:[1,0]
	v_pk_mul_f32 v[4:5], v[4:5], v[34:35] op_sel_hi:[1,0]
	v_pk_mul_f32 v[2:3], v[2:3], v[34:35] op_sel_hi:[1,0]
	v_sub_f32_e32 v58, v58, v186
	v_sub_f32_e32 v59, v59, v186
	s_waitcnt lgkmcnt(0)
	v_mfma_f32_32x32x16_bf16 v[2:17], v[194:197], v[190:193], v[2:17]
	ds_read2_b64 v[194:197], v202 offset0:100 offset1:102
	v_sub_f32_e32 v60, v60, v186
	v_sub_f32_e32 v61, v61, v186
	v_sub_f32_e32 v62, v62, v186
	v_sub_f32_e32 v63, v63, v186
	v_sub_f32_e32 v64, v64, v186
	v_sub_f32_e32 v65, v65, v186
	v_exp_f32_e32 v58, v58
	v_exp_f32_e32 v59, v59
	v_exp_f32_e32 v60, v60
	v_exp_f32_e32 v61, v61
	v_exp_f32_e32 v62, v62
	v_exp_f32_e32 v63, v63
	v_exp_f32_e32 v64, v64
	v_exp_f32_e32 v65, v65
	v_cvt_pk_bf16_f32 v190, v58, v59
	v_cvt_pk_bf16_f32 v191, v60, v61
	v_cvt_pk_bf16_f32 v192, v62, v63
	v_cvt_pk_bf16_f32 v193, v64, v65
	s_waitcnt lgkmcnt(0)
	s_nop 0
	v_mfma_f32_32x32x16_bf16 v[2:17], v[194:197], v[190:193], v[2:17]
	ds_read2_b64 v[194:197], v189 offset0:72 offset1:74
	v_mfma_f32_32x32x16_bf16 v[18:33], v[198:201], v[190:193], v[18:33]
	v_cvt_pk_bf16_f32 v190, v187, v35
	v_cvt_pk_bf16_f32 v191, v36, v37
	v_cvt_pk_bf16_f32 v192, v38, v39
	v_cvt_pk_bf16_f32 v193, v40, v41
	s_waitcnt lgkmcnt(0)
	s_nop 0
	v_mfma_f32_32x32x16_bf16 v[18:33], v[194:197], v[190:193], v[18:33]
	ds_read2_b64 v[194:197], v202 offset0:104 offset1:106
	s_waitcnt lgkmcnt(0)
	v_mfma_f32_32x32x16_bf16 v[2:17], v[194:197], v[190:193], v[2:17]
	ds_read2_b64 v[194:197], v189 offset0:76 offset1:78
	v_cvt_pk_bf16_f32 v190, v42, v43
	v_cvt_pk_bf16_f32 v191, v44, v45
	v_cvt_pk_bf16_f32 v192, v46, v47
	v_cvt_pk_bf16_f32 v193, v48, v49
	s_waitcnt lgkmcnt(0)
	s_nop 0
	v_mfma_f32_32x32x16_bf16 v[18:33], v[194:197], v[190:193], v[18:33]
	ds_read2_b64 v[194:197], v202 offset0:108 offset1:110
	s_waitcnt lgkmcnt(0)
	v_mfma_f32_32x32x16_bf16 v[2:17], v[194:197], v[190:193], v[2:17]
	s_cbranch_vccnz .LBB0_1026
	s_waitcnt vmcnt(3)
	ds_write_b128 v141, v[90:93]
	s_waitcnt vmcnt(2)
	ds_write_b128 v188, v[98:101]
	s_waitcnt vmcnt(0)
	ds_write2_b64 v127, v[110:111], v[112:113] offset1:1
	ds_write2_b64 v128, v[106:107], v[108:109] offset1:1

.LBB0_1028:
	s_nop 0
	s_nop 0
	s_nop 0
	s_nop 0
	s_nop 0
	s_nop 0
	s_nop 0
	s_nop 0
	s_nop 0
	s_nop 0
	s_mov_b64 s[0:1], 0
	s_movk_i32 s61, 0x4000
	s_mov_b32 s52, 0xb000
	s_mov_b32 s62, 0x3b000
	v_readlane_b32 s60, v208, 63
